# row passes, context rows: all split-K partial-slice lines requested once before the compiler's serialized load/wait chain so the chain hits the cache
# baseline (speedup 1.0000x reference)
.LBB0_64:
	v_ashrrev_i32_e32 v0, 6, v0
	v_add_u32_e32 v104, s81, v0
	v_cmp_gt_i32_e32 vcc, s82, v104
	v_lshlrev_b32_e32 v102, 1, v36
	s_and_saveexec_b64 s[24:25], vcc
	s_cbranch_execz .LBB0_70
	s_movk_i32 s2, 0x4000
	v_cmp_gt_i32_e64 s[44:45], s2, v104
	v_readlane_b32 s2, v251, 45
	v_add_u32_e32 v0, 0xffffc000, v104
	v_ashrrev_i32_e32 v105, 31, v104
	v_mov_b32_e32 v36, s2
	v_readlane_b32 s2, v250, 21
	v_cndmask_b32_e64 v3, 0, v105, s[44:45]
	v_cndmask_b32_e64 v2, v0, v104, s[44:45]
	v_mov_b32_e32 v37, s2
	v_readlane_b32 s2, v251, 44
	v_cndmask_b32_e64 v37, v36, v37, s[44:45]
	v_lshlrev_b64 v[2:3], 11, v[2:3]
	v_mov_b32_e32 v36, s2
	v_readlane_b32 s2, v250, 22
	v_mov_b32_e32 v103, v1
	s_nop 0
	v_mov_b32_e32 v38, s2
	v_cndmask_b32_e64 v36, v36, v38, s[44:45]
	v_lshl_add_u64 v[2:3], v[36:37], 0, v[2:3]
	v_lshl_add_u64 v[2:3], v[2:3], 0, v[102:103]
	global_load_dwordx2 v[40:41], v[2:3], off
	global_load_dwordx2 v[38:39], v[2:3], off offset:512
	global_load_dwordx2 v[36:37], v[2:3], off offset:1024
	s_nop 0
	global_load_dwordx2 v[2:3], v[2:3], off offset:1536
	s_movk_i32 s2, 0x3fff
	v_cmp_lt_i32_e64 s[44:45], s2, v104
	s_and_saveexec_b64 s[2:3], s[44:45]
	s_xor_b64 s[34:35], exec, s[2:3]
	s_cbranch_execz .LBB0_67
	v_readlane_b32 s2, v251, 62
	v_mov_b32_e32 v101, v1
	v_readlane_b32 s3, v251, 63
	v_lshlrev_b64 v[44:45], 12, v[0:1]
	s_nop 0
	v_lshl_add_u64 v[42:43], s[2:3], 0, v[100:101]
	v_lshl_add_u64 v[42:43], v[42:43], 0, v[44:45]
	global_load_dwordx4 v[44:47], v[42:43], off
	global_load_dwordx4 v[44:47], v[42:43], off offset:1024
	global_load_dwordx4 v[44:47], v[42:43], off offset:2048
	global_load_dwordx4 v[44:47], v[42:43], off offset:3072
	s_mov_b32 s2, 0x400000
	v_add_co_u32_e64 v64, s[44:45], s2, v42
	s_nop 1
	v_addc_co_u32_e64 v65, s[44:45], 0, v43, s[44:45]
	global_load_dwordx4 v[44:47], v[64:65], off
	global_load_dwordx4 v[44:47], v[64:65], off offset:1024
	global_load_dwordx4 v[44:47], v[64:65], off offset:2048
	global_load_dwordx4 v[44:47], v[64:65], off offset:3072
	s_mov_b32 s2, 0x800000
	v_add_co_u32_e64 v64, s[44:45], s2, v42
	s_nop 1
	v_addc_co_u32_e64 v65, s[44:45], 0, v43, s[44:45]
	global_load_dwordx4 v[44:47], v[64:65], off
	global_load_dwordx4 v[44:47], v[64:65], off offset:1024
	global_load_dwordx4 v[44:47], v[64:65], off offset:2048
	global_load_dwordx4 v[44:47], v[64:65], off offset:3072
	s_mov_b32 s2, 0xc00000
	v_add_co_u32_e64 v64, s[44:45], s2, v42
	s_nop 1
	v_addc_co_u32_e64 v65, s[44:45], 0, v43, s[44:45]
	global_load_dwordx4 v[44:47], v[64:65], off
	global_load_dwordx4 v[44:47], v[64:65], off offset:1024
	global_load_dwordx4 v[44:47], v[64:65], off offset:2048
	global_load_dwordx4 v[44:47], v[64:65], off offset:3072
	s_mov_b32 s2, 0x1000000
	v_add_co_u32_e64 v64, s[44:45], s2, v42
	s_nop 1
	v_addc_co_u32_e64 v65, s[44:45], 0, v43, s[44:45]
	global_load_dwordx4 v[44:47], v[64:65], off
	global_load_dwordx4 v[44:47], v[64:65], off offset:1024
	global_load_dwordx4 v[44:47], v[64:65], off offset:2048
	global_load_dwordx4 v[44:47], v[64:65], off offset:3072
	s_mov_b32 s2, 0x1400000
	v_add_co_u32_e64 v64, s[44:45], s2, v42
	s_nop 1
	v_addc_co_u32_e64 v65, s[44:45], 0, v43, s[44:45]
	global_load_dwordx4 v[44:47], v[64:65], off
	global_load_dwordx4 v[44:47], v[64:65], off offset:1024
	global_load_dwordx4 v[44:47], v[64:65], off offset:2048
	global_load_dwordx4 v[44:47], v[64:65], off offset:3072
	s_mov_b32 s2, 0x1800000
	v_add_co_u32_e64 v64, s[44:45], s2, v42
	s_nop 1
	v_addc_co_u32_e64 v65, s[44:45], 0, v43, s[44:45]
	global_load_dwordx4 v[44:47], v[64:65], off
	global_load_dwordx4 v[44:47], v[64:65], off offset:1024
	global_load_dwordx4 v[44:47], v[64:65], off offset:2048
	global_load_dwordx4 v[44:47], v[64:65], off offset:3072
	global_load_dwordx4 v[44:47], v[42:43], off
	s_mov_b32 s2, 0x400000
	v_add_co_u32_e64 v64, s[44:45], s2, v42
	s_mov_b32 s2, 0x800000
	s_nop 0
	v_addc_co_u32_e64 v65, s[44:45], 0, v43, s[44:45]
	s_waitcnt vmcnt(0)
	v_pk_add_f32 v[48:49], v[46:47], 0 op_sel_hi:[1,0]
	v_pk_add_f32 v[50:51], v[44:45], 0 op_sel_hi:[1,0]
	global_load_dwordx4 v[44:47], v[42:43], off offset:1024
	s_waitcnt vmcnt(0)
	v_pk_add_f32 v[52:53], v[46:47], 0 op_sel_hi:[1,0]
	v_pk_add_f32 v[54:55], v[44:45], 0 op_sel_hi:[1,0]
	global_load_dwordx4 v[44:47], v[42:43], off offset:2048
	s_waitcnt vmcnt(0)
	v_pk_add_f32 v[56:57], v[46:47], 0 op_sel_hi:[1,0]
	v_pk_add_f32 v[58:59], v[44:45], 0 op_sel_hi:[1,0]
	global_load_dwordx4 v[44:47], v[42:43], off offset:3072
	s_waitcnt vmcnt(0)
	v_pk_add_f32 v[60:61], v[46:47], 0 op_sel_hi:[1,0]
	v_pk_add_f32 v[62:63], v[44:45], 0 op_sel_hi:[1,0]
	global_load_dwordx4 v[44:47], v[64:65], off
	s_waitcnt vmcnt(0)
	v_pk_add_f32 v[48:49], v[48:49], v[46:47]
	v_pk_add_f32 v[50:51], v[50:51], v[44:45]
	global_load_dwordx4 v[44:47], v[64:65], off offset:1024
	s_waitcnt vmcnt(0)
	v_pk_add_f32 v[52:53], v[52:53], v[46:47]
	v_pk_add_f32 v[54:55], v[54:55], v[44:45]
	global_load_dwordx4 v[44:47], v[64:65], off offset:2048
	s_waitcnt vmcnt(0)
	v_pk_add_f32 v[56:57], v[56:57], v[46:47]
	v_pk_add_f32 v[58:59], v[58:59], v[44:45]
	global_load_dwordx4 v[44:47], v[64:65], off offset:3072
	v_add_co_u32_e64 v64, s[44:45], s2, v42
	s_mov_b32 s2, 0xc00000
	s_nop 0
	v_addc_co_u32_e64 v65, s[44:45], 0, v43, s[44:45]
	s_waitcnt vmcnt(0)
	v_pk_add_f32 v[60:61], v[60:61], v[46:47]
	v_pk_add_f32 v[62:63], v[62:63], v[44:45]
	global_load_dwordx4 v[44:47], v[64:65], off
	s_waitcnt vmcnt(0)
	v_pk_add_f32 v[48:49], v[48:49], v[46:47]
	v_pk_add_f32 v[50:51], v[50:51], v[44:45]
	global_load_dwordx4 v[44:47], v[64:65], off offset:1024
	s_waitcnt vmcnt(0)
	v_pk_add_f32 v[52:53], v[52:53], v[46:47]
	v_pk_add_f32 v[54:55], v[54:55], v[44:45]
	global_load_dwordx4 v[44:47], v[64:65], off offset:2048
	s_waitcnt vmcnt(0)
	v_pk_add_f32 v[56:57], v[56:57], v[46:47]
	v_pk_add_f32 v[58:59], v[58:59], v[44:45]
	global_load_dwordx4 v[44:47], v[64:65], off offset:3072
	v_add_co_u32_e64 v64, s[44:45], s2, v42
	s_mov_b32 s2, 0x1000000
	s_nop 0
	v_addc_co_u32_e64 v65, s[44:45], 0, v43, s[44:45]
	s_waitcnt vmcnt(0)
	v_pk_add_f32 v[60:61], v[60:61], v[46:47]
	v_pk_add_f32 v[62:63], v[62:63], v[44:45]
	global_load_dwordx4 v[44:47], v[64:65], off
	s_waitcnt vmcnt(0)
	v_pk_add_f32 v[48:49], v[48:49], v[46:47]
	v_pk_add_f32 v[50:51], v[50:51], v[44:45]
	global_load_dwordx4 v[44:47], v[64:65], off offset:1024
	s_waitcnt vmcnt(0)
	v_pk_add_f32 v[52:53], v[52:53], v[46:47]
	v_pk_add_f32 v[54:55], v[54:55], v[44:45]
	global_load_dwordx4 v[44:47], v[64:65], off offset:2048
	s_waitcnt vmcnt(0)
	v_pk_add_f32 v[56:57], v[56:57], v[46:47]
	v_pk_add_f32 v[58:59], v[58:59], v[44:45]
	global_load_dwordx4 v[44:47], v[64:65], off offset:3072
	v_add_co_u32_e64 v64, s[44:45], s2, v42
	s_mov_b32 s2, 0x1400000
	s_nop 0
	v_addc_co_u32_e64 v65, s[44:45], 0, v43, s[44:45]
	s_waitcnt vmcnt(0)
	v_pk_add_f32 v[60:61], v[60:61], v[46:47]
	v_pk_add_f32 v[62:63], v[62:63], v[44:45]
	global_load_dwordx4 v[44:47], v[64:65], off
	s_waitcnt vmcnt(0)
	v_pk_add_f32 v[48:49], v[48:49], v[46:47]
	v_pk_add_f32 v[50:51], v[50:51], v[44:45]
	global_load_dwordx4 v[44:47], v[64:65], off offset:1024
	s_waitcnt vmcnt(0)
	v_pk_add_f32 v[52:53], v[52:53], v[46:47]
	v_pk_add_f32 v[54:55], v[54:55], v[44:45]
	global_load_dwordx4 v[44:47], v[64:65], off offset:2048
	s_waitcnt vmcnt(0)
	v_pk_add_f32 v[56:57], v[56:57], v[46:47]
	v_pk_add_f32 v[58:59], v[58:59], v[44:45]
	global_load_dwordx4 v[44:47], v[64:65], off offset:3072
	v_add_co_u32_e64 v64, s[44:45], s2, v42
	s_mov_b32 s2, 0x1800000
	s_nop 0
	v_addc_co_u32_e64 v65, s[44:45], 0, v43, s[44:45]
	v_add_co_u32_e64 v42, s[44:45], s2, v42
	s_waitcnt vmcnt(0)
	v_pk_add_f32 v[60:61], v[60:61], v[46:47]
	v_pk_add_f32 v[62:63], v[62:63], v[44:45]
	global_load_dwordx4 v[44:47], v[64:65], off
	v_addc_co_u32_e64 v43, s[44:45], 0, v43, s[44:45]
	s_waitcnt vmcnt(0)
	v_pk_add_f32 v[66:67], v[48:49], v[46:47]
	v_pk_add_f32 v[68:69], v[50:51], v[44:45]
	global_load_dwordx4 v[44:47], v[64:65], off offset:1024
	global_load_dwordx4 v[48:51], v[42:43], off
	s_waitcnt vmcnt(1)
	v_pk_add_f32 v[52:53], v[52:53], v[46:47]
	v_pk_add_f32 v[54:55], v[54:55], v[44:45]
	global_load_dwordx4 v[44:47], v[64:65], off offset:2048
	s_waitcnt vmcnt(1)
	v_pk_add_f32 v[92:93], v[66:67], v[50:51]
	v_pk_add_f32 v[90:91], v[68:69], v[48:49]
	global_load_dwordx4 v[48:51], v[42:43], off offset:1024
	s_waitcnt vmcnt(1)
	v_pk_add_f32 v[56:57], v[56:57], v[46:47]
	v_pk_add_f32 v[58:59], v[58:59], v[44:45]
	global_load_dwordx4 v[44:47], v[64:65], off offset:3072
	s_waitcnt vmcnt(1)
	v_pk_add_f32 v[96:97], v[52:53], v[50:51]
	v_pk_add_f32 v[86:87], v[54:55], v[48:49]
	global_load_dwordx4 v[48:51], v[42:43], off offset:2048
	s_waitcnt vmcnt(1)
	v_pk_add_f32 v[46:47], v[60:61], v[46:47]
	v_pk_add_f32 v[44:45], v[62:63], v[44:45]
	s_waitcnt vmcnt(0)
	v_pk_add_f32 v[88:89], v[56:57], v[50:51]
	v_pk_add_f32 v[84:85], v[58:59], v[48:49]
	global_load_dwordx4 v[48:51], v[42:43], off offset:3072
	s_waitcnt vmcnt(0)
	v_pk_add_f32 v[126:127], v[46:47], v[50:51]
	v_pk_add_f32 v[124:125], v[44:45], v[48:49]

.LBB0_70:
	s_or_b64 exec, exec, s[24:25]
	v_add_u32_e32 v42, s71, v104
	v_cmp_gt_i32_e64 s[44:45], s82, v42
	s_and_saveexec_b64 s[24:25], s[44:45]
	s_cbranch_execz .LBB0_76
	s_movk_i32 s2, 0x4000
	v_cmp_gt_i32_e64 s[44:45], s2, v42
	v_readlane_b32 s2, v251, 45
	v_add_u32_e32 v0, 0xffffc000, v42
	v_ashrrev_i32_e32 v43, 31, v42
	v_mov_b32_e32 v36, s2
	v_readlane_b32 s2, v250, 21
	v_cndmask_b32_e64 v3, 0, v43, s[44:45]
	v_cndmask_b32_e64 v2, v0, v42, s[44:45]
	v_mov_b32_e32 v37, s2
	v_readlane_b32 s2, v251, 44
	v_cndmask_b32_e64 v37, v36, v37, s[44:45]
	v_lshlrev_b64 v[2:3], 11, v[2:3]
	v_mov_b32_e32 v36, s2
	v_readlane_b32 s2, v250, 22
	v_mov_b32_e32 v103, v1
	s_nop 0
	v_mov_b32_e32 v38, s2
	v_cndmask_b32_e64 v36, v36, v38, s[44:45]
	v_lshl_add_u64 v[2:3], v[36:37], 0, v[2:3]
	v_lshl_add_u64 v[2:3], v[2:3], 0, v[102:103]
	global_load_dwordx2 v[40:41], v[2:3], off
	global_load_dwordx2 v[38:39], v[2:3], off offset:512
	global_load_dwordx2 v[36:37], v[2:3], off offset:1024
	s_nop 0
	global_load_dwordx2 v[2:3], v[2:3], off offset:1536
	s_movk_i32 s2, 0x3fff
	v_cmp_lt_i32_e64 s[44:45], s2, v42
	s_and_saveexec_b64 s[2:3], s[44:45]
	s_xor_b64 s[34:35], exec, s[2:3]
	s_cbranch_execz .LBB0_73
	v_readlane_b32 s2, v251, 62
	v_mov_b32_e32 v101, v1
	v_readlane_b32 s3, v251, 63
	v_lshlrev_b64 v[44:45], 12, v[0:1]
	s_nop 0
	v_lshl_add_u64 v[42:43], s[2:3], 0, v[100:101]
	v_lshl_add_u64 v[42:43], v[42:43], 0, v[44:45]
	global_load_dwordx4 v[44:47], v[42:43], off
	global_load_dwordx4 v[44:47], v[42:43], off offset:1024
	global_load_dwordx4 v[44:47], v[42:43], off offset:2048
	global_load_dwordx4 v[44:47], v[42:43], off offset:3072
	s_mov_b32 s2, 0x400000
	v_add_co_u32_e64 v64, s[44:45], s2, v42
	s_nop 1
	v_addc_co_u32_e64 v65, s[44:45], 0, v43, s[44:45]
	global_load_dwordx4 v[44:47], v[64:65], off
	global_load_dwordx4 v[44:47], v[64:65], off offset:1024
	global_load_dwordx4 v[44:47], v[64:65], off offset:2048
	global_load_dwordx4 v[44:47], v[64:65], off offset:3072
	s_mov_b32 s2, 0x800000
	v_add_co_u32_e64 v64, s[44:45], s2, v42
	s_nop 1
	v_addc_co_u32_e64 v65, s[44:45], 0, v43, s[44:45]
	global_load_dwordx4 v[44:47], v[64:65], off
	global_load_dwordx4 v[44:47], v[64:65], off offset:1024
	global_load_dwordx4 v[44:47], v[64:65], off offset:2048
	global_load_dwordx4 v[44:47], v[64:65], off offset:3072
	s_mov_b32 s2, 0xc00000
	v_add_co_u32_e64 v64, s[44:45], s2, v42
	s_nop 1
	v_addc_co_u32_e64 v65, s[44:45], 0, v43, s[44:45]
	global_load_dwordx4 v[44:47], v[64:65], off
	global_load_dwordx4 v[44:47], v[64:65], off offset:1024
	global_load_dwordx4 v[44:47], v[64:65], off offset:2048
	global_load_dwordx4 v[44:47], v[64:65], off offset:3072
	s_mov_b32 s2, 0x1000000
	v_add_co_u32_e64 v64, s[44:45], s2, v42
	s_nop 1
	v_addc_co_u32_e64 v65, s[44:45], 0, v43, s[44:45]
	global_load_dwordx4 v[44:47], v[64:65], off
	global_load_dwordx4 v[44:47], v[64:65], off offset:1024
	global_load_dwordx4 v[44:47], v[64:65], off offset:2048
	global_load_dwordx4 v[44:47], v[64:65], off offset:3072
	s_mov_b32 s2, 0x1400000
	v_add_co_u32_e64 v64, s[44:45], s2, v42
	s_nop 1
	v_addc_co_u32_e64 v65, s[44:45], 0, v43, s[44:45]
	global_load_dwordx4 v[44:47], v[64:65], off
	global_load_dwordx4 v[44:47], v[64:65], off offset:1024
	global_load_dwordx4 v[44:47], v[64:65], off offset:2048
	global_load_dwordx4 v[44:47], v[64:65], off offset:3072
	s_mov_b32 s2, 0x1800000
	v_add_co_u32_e64 v64, s[44:45], s2, v42
	s_nop 1
	v_addc_co_u32_e64 v65, s[44:45], 0, v43, s[44:45]
	global_load_dwordx4 v[44:47], v[64:65], off
	global_load_dwordx4 v[44:47], v[64:65], off offset:1024
	global_load_dwordx4 v[44:47], v[64:65], off offset:2048
	global_load_dwordx4 v[44:47], v[64:65], off offset:3072
	global_load_dwordx4 v[44:47], v[42:43], off
	s_mov_b32 s2, 0x400000
	v_add_co_u32_e64 v64, s[44:45], s2, v42
	s_mov_b32 s2, 0x800000
	s_nop 0
	v_addc_co_u32_e64 v65, s[44:45], 0, v43, s[44:45]
	s_waitcnt vmcnt(0)
	v_pk_add_f32 v[48:49], v[46:47], 0 op_sel_hi:[1,0]
	v_pk_add_f32 v[50:51], v[44:45], 0 op_sel_hi:[1,0]
	global_load_dwordx4 v[44:47], v[42:43], off offset:1024
	s_waitcnt vmcnt(0)
	v_pk_add_f32 v[52:53], v[46:47], 0 op_sel_hi:[1,0]
	v_pk_add_f32 v[54:55], v[44:45], 0 op_sel_hi:[1,0]
	global_load_dwordx4 v[44:47], v[42:43], off offset:2048
	s_waitcnt vmcnt(0)
	v_pk_add_f32 v[56:57], v[46:47], 0 op_sel_hi:[1,0]
	v_pk_add_f32 v[58:59], v[44:45], 0 op_sel_hi:[1,0]
	global_load_dwordx4 v[44:47], v[42:43], off offset:3072
	s_waitcnt vmcnt(0)
	v_pk_add_f32 v[60:61], v[46:47], 0 op_sel_hi:[1,0]
	v_pk_add_f32 v[62:63], v[44:45], 0 op_sel_hi:[1,0]
	global_load_dwordx4 v[44:47], v[64:65], off
	s_waitcnt vmcnt(0)
	v_pk_add_f32 v[48:49], v[48:49], v[46:47]
	v_pk_add_f32 v[50:51], v[50:51], v[44:45]
	global_load_dwordx4 v[44:47], v[64:65], off offset:1024
	s_waitcnt vmcnt(0)
	v_pk_add_f32 v[52:53], v[52:53], v[46:47]
	v_pk_add_f32 v[54:55], v[54:55], v[44:45]
	global_load_dwordx4 v[44:47], v[64:65], off offset:2048
	s_waitcnt vmcnt(0)
	v_pk_add_f32 v[56:57], v[56:57], v[46:47]
	v_pk_add_f32 v[58:59], v[58:59], v[44:45]
	global_load_dwordx4 v[44:47], v[64:65], off offset:3072
	v_add_co_u32_e64 v64, s[44:45], s2, v42
	s_mov_b32 s2, 0xc00000
	s_nop 0
	v_addc_co_u32_e64 v65, s[44:45], 0, v43, s[44:45]
	s_waitcnt vmcnt(0)
	v_pk_add_f32 v[60:61], v[60:61], v[46:47]
	v_pk_add_f32 v[62:63], v[62:63], v[44:45]
	global_load_dwordx4 v[44:47], v[64:65], off
	s_waitcnt vmcnt(0)
	v_pk_add_f32 v[48:49], v[48:49], v[46:47]
	v_pk_add_f32 v[50:51], v[50:51], v[44:45]
	global_load_dwordx4 v[44:47], v[64:65], off offset:1024
	s_waitcnt vmcnt(0)
	v_pk_add_f32 v[52:53], v[52:53], v[46:47]
	v_pk_add_f32 v[54:55], v[54:55], v[44:45]
	global_load_dwordx4 v[44:47], v[64:65], off offset:2048
	s_waitcnt vmcnt(0)
	v_pk_add_f32 v[56:57], v[56:57], v[46:47]
	v_pk_add_f32 v[58:59], v[58:59], v[44:45]
	global_load_dwordx4 v[44:47], v[64:65], off offset:3072
	v_add_co_u32_e64 v64, s[44:45], s2, v42
	s_mov_b32 s2, 0x1000000
	s_nop 0
	v_addc_co_u32_e64 v65, s[44:45], 0, v43, s[44:45]
	s_waitcnt vmcnt(0)
	v_pk_add_f32 v[60:61], v[60:61], v[46:47]
	v_pk_add_f32 v[62:63], v[62:63], v[44:45]
	global_load_dwordx4 v[44:47], v[64:65], off
	s_waitcnt vmcnt(0)
	v_pk_add_f32 v[48:49], v[48:49], v[46:47]
	v_pk_add_f32 v[50:51], v[50:51], v[44:45]
	global_load_dwordx4 v[44:47], v[64:65], off offset:1024
	s_waitcnt vmcnt(0)
	v_pk_add_f32 v[52:53], v[52:53], v[46:47]
	v_pk_add_f32 v[54:55], v[54:55], v[44:45]
	global_load_dwordx4 v[44:47], v[64:65], off offset:2048
	s_waitcnt vmcnt(0)
	v_pk_add_f32 v[56:57], v[56:57], v[46:47]
	v_pk_add_f32 v[58:59], v[58:59], v[44:45]
	global_load_dwordx4 v[44:47], v[64:65], off offset:3072
	v_add_co_u32_e64 v64, s[44:45], s2, v42
	s_mov_b32 s2, 0x1400000
	s_nop 0
	v_addc_co_u32_e64 v65, s[44:45], 0, v43, s[44:45]
	s_waitcnt vmcnt(0)
	v_pk_add_f32 v[60:61], v[60:61], v[46:47]
	v_pk_add_f32 v[62:63], v[62:63], v[44:45]
	global_load_dwordx4 v[44:47], v[64:65], off
	s_waitcnt vmcnt(0)
	v_pk_add_f32 v[48:49], v[48:49], v[46:47]
	v_pk_add_f32 v[50:51], v[50:51], v[44:45]
	global_load_dwordx4 v[44:47], v[64:65], off offset:1024
	s_waitcnt vmcnt(0)
	v_pk_add_f32 v[52:53], v[52:53], v[46:47]
	v_pk_add_f32 v[54:55], v[54:55], v[44:45]
	global_load_dwordx4 v[44:47], v[64:65], off offset:2048
	s_waitcnt vmcnt(0)
	v_pk_add_f32 v[56:57], v[56:57], v[46:47]
	v_pk_add_f32 v[58:59], v[58:59], v[44:45]
	global_load_dwordx4 v[44:47], v[64:65], off offset:3072
	v_add_co_u32_e64 v64, s[44:45], s2, v42
	s_mov_b32 s2, 0x1800000
	s_nop 0
	v_addc_co_u32_e64 v65, s[44:45], 0, v43, s[44:45]
	v_add_co_u32_e64 v42, s[44:45], s2, v42
	s_waitcnt vmcnt(0)
	v_pk_add_f32 v[60:61], v[60:61], v[46:47]
	v_pk_add_f32 v[62:63], v[62:63], v[44:45]
	global_load_dwordx4 v[44:47], v[64:65], off
	v_addc_co_u32_e64 v43, s[44:45], 0, v43, s[44:45]
	s_waitcnt vmcnt(0)
	v_pk_add_f32 v[66:67], v[48:49], v[46:47]
	v_pk_add_f32 v[68:69], v[50:51], v[44:45]
	global_load_dwordx4 v[44:47], v[64:65], off offset:1024
	global_load_dwordx4 v[48:51], v[42:43], off
	s_waitcnt vmcnt(1)
	v_pk_add_f32 v[52:53], v[52:53], v[46:47]
	v_pk_add_f32 v[54:55], v[54:55], v[44:45]
	global_load_dwordx4 v[44:47], v[64:65], off offset:2048
	s_waitcnt vmcnt(1)
	v_pk_add_f32 v[114:115], v[66:67], v[50:51]
	v_pk_add_f32 v[112:113], v[68:69], v[48:49]
	global_load_dwordx4 v[48:51], v[42:43], off offset:1024
	s_waitcnt vmcnt(1)
	v_pk_add_f32 v[56:57], v[56:57], v[46:47]
	v_pk_add_f32 v[58:59], v[58:59], v[44:45]
	global_load_dwordx4 v[44:47], v[64:65], off offset:3072
	s_waitcnt vmcnt(1)
	v_pk_add_f32 v[118:119], v[52:53], v[50:51]
	v_pk_add_f32 v[116:117], v[54:55], v[48:49]
	global_load_dwordx4 v[48:51], v[42:43], off offset:2048
	s_waitcnt vmcnt(1)
	v_pk_add_f32 v[46:47], v[60:61], v[46:47]
	v_pk_add_f32 v[44:45], v[62:63], v[44:45]
	s_waitcnt vmcnt(0)
	v_pk_add_f32 v[122:123], v[56:57], v[50:51]
	v_pk_add_f32 v[120:121], v[58:59], v[48:49]
	global_load_dwordx4 v[48:51], v[42:43], off offset:3072
	s_waitcnt vmcnt(0)
	v_pk_add_f32 v[142:143], v[46:47], v[50:51]
	v_pk_add_f32 v[140:141], v[44:45], v[48:49]

.LBB0_79:
	v_add_u32_e32 v190, s73, v104
	v_cmp_gt_i32_e32 vcc, s82, v190
	v_mov_b32_e32 v209, v138
	v_mov_b32_e32 v210, v139
	v_mov_b32_e32 v211, v94
	v_mov_b32_e32 v212, v95
	v_mov_b32_e32 v213, v136
	v_mov_b32_e32 v214, v137
	v_mov_b32_e32 v215, v98
	v_mov_b32_e32 v216, v99
	v_mov_b32_e32 v217, v132
	v_mov_b32_e32 v218, v133
	v_mov_b32_e32 v219, v134
	v_mov_b32_e32 v220, v135
	v_mov_b32_e32 v221, v128
	v_mov_b32_e32 v222, v129
	v_mov_b32_e32 v223, v130
	v_mov_b32_e32 v224, v131
	v_mov_b32_e32 v168, v90
	v_mov_b32_e32 v169, v91
	v_mov_b32_e32 v2, v92
	v_mov_b32_e32 v3, v93
	v_mov_b32_e32 v172, v86
	v_mov_b32_e32 v173, v87
	v_mov_b32_e32 v170, v96
	v_mov_b32_e32 v171, v97
	v_mov_b32_e32 v176, v84
	v_mov_b32_e32 v177, v85
	v_mov_b32_e32 v174, v88
	v_mov_b32_e32 v175, v89
	v_mov_b32_e32 v180, v124
	v_mov_b32_e32 v181, v125
	v_mov_b32_e32 v178, v126
	v_mov_b32_e32 v179, v127
	s_and_saveexec_b64 s[44:45], vcc
	s_cbranch_execz .LBB0_85
	s_movk_i32 s2, 0x4000
	v_cmp_gt_i32_e32 vcc, s2, v190
	v_readlane_b32 s2, v251, 45
	v_add_u32_e32 v0, 0xffffc000, v190
	v_ashrrev_i32_e32 v191, 31, v190
	v_mov_b32_e32 v101, s2
	v_readlane_b32 s2, v250, 21
	v_cndmask_b32_e32 v3, 0, v191, vcc
	v_cndmask_b32_e32 v2, v0, v190, vcc
	v_mov_b32_e32 v103, s2
	v_readlane_b32 s2, v251, 44
	v_cndmask_b32_e32 v149, v101, v103, vcc
	v_lshlrev_b64 v[2:3], 11, v[2:3]
	v_mov_b32_e32 v101, s2
	v_readlane_b32 s2, v250, 22
	s_nop 1
	v_mov_b32_e32 v103, s2
	v_cndmask_b32_e32 v148, v101, v103, vcc
	v_lshl_add_u64 v[2:3], v[148:149], 0, v[2:3]
	v_mov_b32_e32 v103, v1
	v_lshl_add_u64 v[2:3], v[2:3], 0, v[102:103]
	global_load_dwordx2 v[188:189], v[2:3], off
	global_load_dwordx2 v[186:187], v[2:3], off offset:512
	global_load_dwordx2 v[184:185], v[2:3], off offset:1024
	global_load_dwordx2 v[182:183], v[2:3], off offset:1536
	s_movk_i32 s2, 0x3fff
	v_cmp_lt_i32_e32 vcc, s2, v190
	s_and_saveexec_b64 s[2:3], vcc
	s_xor_b64 s[46:47], exec, s[2:3]
	s_cbranch_execz .LBB0_82
	v_lshlrev_b64 v[2:3], 12, v[0:1]
	v_lshl_add_u64 v[2:3], v[106:107], 0, v[2:3]
	global_load_dwordx4 v[168:171], v[2:3], off
	global_load_dwordx4 v[168:171], v[2:3], off offset:1024
	global_load_dwordx4 v[168:171], v[2:3], off offset:2048
	global_load_dwordx4 v[168:171], v[2:3], off offset:3072
	s_mov_b32 s2, 0x400000
	v_add_co_u32_e32 v190, vcc, s2, v2
	s_nop 1
	v_addc_co_u32_e32 v191, vcc, 0, v3, vcc
	global_load_dwordx4 v[168:171], v[190:191], off
	global_load_dwordx4 v[168:171], v[190:191], off offset:1024
	global_load_dwordx4 v[168:171], v[190:191], off offset:2048
	global_load_dwordx4 v[168:171], v[190:191], off offset:3072
	s_mov_b32 s2, 0x800000
	v_add_co_u32_e32 v190, vcc, s2, v2
	s_nop 1
	v_addc_co_u32_e32 v191, vcc, 0, v3, vcc
	global_load_dwordx4 v[168:171], v[190:191], off
	global_load_dwordx4 v[168:171], v[190:191], off offset:1024
	global_load_dwordx4 v[168:171], v[190:191], off offset:2048
	global_load_dwordx4 v[168:171], v[190:191], off offset:3072
	s_mov_b32 s2, 0xc00000
	v_add_co_u32_e32 v190, vcc, s2, v2
	s_nop 1
	v_addc_co_u32_e32 v191, vcc, 0, v3, vcc
	global_load_dwordx4 v[168:171], v[190:191], off
	global_load_dwordx4 v[168:171], v[190:191], off offset:1024
	global_load_dwordx4 v[168:171], v[190:191], off offset:2048
	global_load_dwordx4 v[168:171], v[190:191], off offset:3072
	s_mov_b32 s2, 0x1000000
	v_add_co_u32_e32 v190, vcc, s2, v2
	s_nop 1
	v_addc_co_u32_e32 v191, vcc, 0, v3, vcc
	global_load_dwordx4 v[168:171], v[190:191], off
	global_load_dwordx4 v[168:171], v[190:191], off offset:1024
	global_load_dwordx4 v[168:171], v[190:191], off offset:2048
	global_load_dwordx4 v[168:171], v[190:191], off offset:3072
	s_mov_b32 s2, 0x1400000
	v_add_co_u32_e32 v190, vcc, s2, v2
	s_nop 1
	v_addc_co_u32_e32 v191, vcc, 0, v3, vcc
	global_load_dwordx4 v[168:171], v[190:191], off
	global_load_dwordx4 v[168:171], v[190:191], off offset:1024
	global_load_dwordx4 v[168:171], v[190:191], off offset:2048
	global_load_dwordx4 v[168:171], v[190:191], off offset:3072
	s_mov_b32 s2, 0x1800000
	v_add_co_u32_e32 v190, vcc, s2, v2
	s_nop 1
	v_addc_co_u32_e32 v191, vcc, 0, v3, vcc
	global_load_dwordx4 v[168:171], v[190:191], off
	global_load_dwordx4 v[168:171], v[190:191], off offset:1024
	global_load_dwordx4 v[168:171], v[190:191], off offset:2048
	global_load_dwordx4 v[168:171], v[190:191], off offset:3072
	global_load_dwordx4 v[168:171], v[2:3], off
	s_mov_b32 s2, 0x400000
	v_add_co_u32_e32 v190, vcc, s2, v2
	s_mov_b32 s2, 0x800000
	s_nop 0
	v_addc_co_u32_e32 v191, vcc, 0, v3, vcc
	s_waitcnt vmcnt(0)
	v_pk_add_f32 v[148:149], v[170:171], 0 op_sel_hi:[1,0]
	v_pk_add_f32 v[152:153], v[168:169], 0 op_sel_hi:[1,0]
	global_load_dwordx4 v[168:171], v[2:3], off offset:1024
	s_waitcnt vmcnt(0)
	v_pk_add_f32 v[154:155], v[170:171], 0 op_sel_hi:[1,0]
	v_pk_add_f32 v[172:173], v[168:169], 0 op_sel_hi:[1,0]
	global_load_dwordx4 v[168:171], v[2:3], off offset:2048
	s_waitcnt vmcnt(0)
	v_pk_add_f32 v[174:175], v[170:171], 0 op_sel_hi:[1,0]
	v_pk_add_f32 v[176:177], v[168:169], 0 op_sel_hi:[1,0]
	global_load_dwordx4 v[168:171], v[2:3], off offset:3072
	s_waitcnt vmcnt(0)
	v_pk_add_f32 v[178:179], v[170:171], 0 op_sel_hi:[1,0]
	v_pk_add_f32 v[180:181], v[168:169], 0 op_sel_hi:[1,0]
	global_load_dwordx4 v[168:171], v[190:191], off
	s_waitcnt vmcnt(0)
	v_pk_add_f32 v[148:149], v[148:149], v[170:171]
	v_pk_add_f32 v[152:153], v[152:153], v[168:169]
	global_load_dwordx4 v[168:171], v[190:191], off offset:1024
	s_waitcnt vmcnt(0)
	v_pk_add_f32 v[154:155], v[154:155], v[170:171]
	v_pk_add_f32 v[172:173], v[172:173], v[168:169]
	global_load_dwordx4 v[168:171], v[190:191], off offset:2048
	s_waitcnt vmcnt(0)
	v_pk_add_f32 v[174:175], v[174:175], v[170:171]
	v_pk_add_f32 v[176:177], v[176:177], v[168:169]
	global_load_dwordx4 v[168:171], v[190:191], off offset:3072
	v_add_co_u32_e32 v190, vcc, s2, v2
	s_mov_b32 s2, 0xc00000
	s_nop 0
	v_addc_co_u32_e32 v191, vcc, 0, v3, vcc
	s_waitcnt vmcnt(0)
	v_pk_add_f32 v[178:179], v[178:179], v[170:171]
	v_pk_add_f32 v[180:181], v[180:181], v[168:169]
	global_load_dwordx4 v[168:171], v[190:191], off
	s_waitcnt vmcnt(0)
	v_pk_add_f32 v[148:149], v[148:149], v[170:171]
	v_pk_add_f32 v[152:153], v[152:153], v[168:169]
	global_load_dwordx4 v[168:171], v[190:191], off offset:1024
	s_waitcnt vmcnt(0)
	v_pk_add_f32 v[154:155], v[154:155], v[170:171]
	v_pk_add_f32 v[172:173], v[172:173], v[168:169]
	global_load_dwordx4 v[168:171], v[190:191], off offset:2048
	s_waitcnt vmcnt(0)
	v_pk_add_f32 v[174:175], v[174:175], v[170:171]
	v_pk_add_f32 v[176:177], v[176:177], v[168:169]
	global_load_dwordx4 v[168:171], v[190:191], off offset:3072
	v_add_co_u32_e32 v190, vcc, s2, v2
	s_mov_b32 s2, 0x1000000
	s_nop 0
	v_addc_co_u32_e32 v191, vcc, 0, v3, vcc
	s_waitcnt vmcnt(0)
	v_pk_add_f32 v[178:179], v[178:179], v[170:171]
	v_pk_add_f32 v[180:181], v[180:181], v[168:169]
	global_load_dwordx4 v[168:171], v[190:191], off
	s_waitcnt vmcnt(0)
	v_pk_add_f32 v[148:149], v[148:149], v[170:171]
	v_pk_add_f32 v[152:153], v[152:153], v[168:169]
	global_load_dwordx4 v[168:171], v[190:191], off offset:1024
	s_waitcnt vmcnt(0)
	v_pk_add_f32 v[154:155], v[154:155], v[170:171]
	v_pk_add_f32 v[172:173], v[172:173], v[168:169]
	global_load_dwordx4 v[168:171], v[190:191], off offset:2048
	s_waitcnt vmcnt(0)
	v_pk_add_f32 v[174:175], v[174:175], v[170:171]
	v_pk_add_f32 v[176:177], v[176:177], v[168:169]
	global_load_dwordx4 v[168:171], v[190:191], off offset:3072
	v_add_co_u32_e32 v190, vcc, s2, v2
	s_mov_b32 s2, 0x1400000
	s_nop 0
	v_addc_co_u32_e32 v191, vcc, 0, v3, vcc
	s_waitcnt vmcnt(0)
	v_pk_add_f32 v[178:179], v[178:179], v[170:171]
	v_pk_add_f32 v[180:181], v[180:181], v[168:169]
	global_load_dwordx4 v[168:171], v[190:191], off
	s_waitcnt vmcnt(0)
	v_pk_add_f32 v[148:149], v[148:149], v[170:171]
	v_pk_add_f32 v[152:153], v[152:153], v[168:169]
	global_load_dwordx4 v[168:171], v[190:191], off offset:1024
	s_waitcnt vmcnt(0)
	v_pk_add_f32 v[154:155], v[154:155], v[170:171]
	v_pk_add_f32 v[172:173], v[172:173], v[168:169]
	global_load_dwordx4 v[168:171], v[190:191], off offset:2048
	s_waitcnt vmcnt(0)
	v_pk_add_f32 v[174:175], v[174:175], v[170:171]
	v_pk_add_f32 v[176:177], v[176:177], v[168:169]
	global_load_dwordx4 v[168:171], v[190:191], off offset:3072
	v_add_co_u32_e32 v190, vcc, s2, v2
	s_mov_b32 s2, 0x1800000
	s_nop 0
	v_addc_co_u32_e32 v191, vcc, 0, v3, vcc
	v_add_co_u32_e32 v196, vcc, s2, v2
	s_waitcnt vmcnt(0)
	v_pk_add_f32 v[178:179], v[178:179], v[170:171]
	v_pk_add_f32 v[180:181], v[180:181], v[168:169]
	global_load_dwordx4 v[168:171], v[190:191], off
	v_addc_co_u32_e32 v197, vcc, 0, v3, vcc
	s_waitcnt vmcnt(0)
	v_pk_add_f32 v[148:149], v[148:149], v[170:171]
	v_pk_add_f32 v[152:153], v[152:153], v[168:169]
	global_load_dwordx4 v[168:171], v[190:191], off offset:1024
	s_waitcnt vmcnt(0)
	v_pk_add_f32 v[154:155], v[154:155], v[170:171]
	v_pk_add_f32 v[192:193], v[172:173], v[168:169]
	global_load_dwordx4 v[168:171], v[190:191], off offset:2048
	s_waitcnt vmcnt(0)
	v_pk_add_f32 v[194:195], v[174:175], v[170:171]
	v_pk_add_f32 v[176:177], v[176:177], v[168:169]
	global_load_dwordx4 v[168:171], v[190:191], off offset:3072
	global_load_dwordx4 v[172:175], v[196:197], off offset:1024
	s_waitcnt vmcnt(1)
	v_pk_add_f32 v[178:179], v[178:179], v[170:171]
	v_pk_add_f32 v[180:181], v[180:181], v[168:169]
	global_load_dwordx4 v[168:171], v[196:197], off
	s_waitcnt vmcnt(1)
	v_pk_add_f32 v[172:173], v[192:193], v[172:173]
	global_load_dwordx4 v[190:193], v[196:197], off offset:2048
	s_waitcnt vmcnt(1)
	v_pk_add_f32 v[2:3], v[148:149], v[170:171]
	v_pk_add_f32 v[170:171], v[154:155], v[174:175]
	s_waitcnt vmcnt(0)
	v_pk_add_f32 v[174:175], v[194:195], v[192:193]
	v_pk_add_f32 v[176:177], v[176:177], v[190:191]
	global_load_dwordx4 v[190:193], v[196:197], off offset:3072
	v_pk_add_f32 v[168:169], v[152:153], v[168:169]
	s_waitcnt vmcnt(0)
	v_pk_add_f32 v[178:179], v[178:179], v[192:193]
	v_pk_add_f32 v[180:181], v[180:181], v[190:191]

.LBB0_85:
	s_or_b64 exec, exec, s[44:45]
	v_readlane_b32 s2, v250, 7
	v_mov_b32_e32 v196, v140
	v_mov_b32_e32 v197, v141
	v_add_u32_e32 v206, s2, v104
	v_cmp_gt_i32_e32 vcc, s82, v206
	v_mov_b32_e32 v194, v142
	v_mov_b32_e32 v195, v143
	v_mov_b32_e32 v192, v120
	v_mov_b32_e32 v193, v121
	v_mov_b32_e32 v190, v122
	v_mov_b32_e32 v191, v123
	v_mov_b32_e32 v188, v116
	v_mov_b32_e32 v189, v117
	v_mov_b32_e32 v186, v118
	v_mov_b32_e32 v187, v119
	v_mov_b32_e32 v184, v112
	v_mov_b32_e32 v185, v113
	v_mov_b32_e32 v182, v114
	v_mov_b32_e32 v183, v115
	v_mov_b32_e32 v0, v144
	v_mov_b32_e32 v198, v145
	v_mov_b32_e32 v200, v146
	v_mov_b32_e32 v199, v147
	v_mov_b32_e32 v202, v156
	v_mov_b32_e32 v203, v157
	v_mov_b32_e32 v204, v158
	v_mov_b32_e32 v201, v159
	v_mov_b32_e32 v205, v160
	v_mov_b32_e32 v207, v161
	v_mov_b32_e32 v225, v162
	v_mov_b32_e32 v226, v163
	v_mov_b32_e32 v227, v164
	v_mov_b32_e32 v228, v165
	v_mov_b32_e32 v229, v166
	v_mov_b32_e32 v230, v167
	s_and_saveexec_b64 s[44:45], vcc
	s_cbranch_execz .LBB0_91
	s_movk_i32 s2, 0x4000
	v_cmp_gt_i32_e32 vcc, s2, v206
	v_readlane_b32 s2, v251, 45
	v_add_u32_e32 v0, 0xffffc000, v206
	v_ashrrev_i32_e32 v207, 31, v206
	v_mov_b32_e32 v101, s2
	v_readlane_b32 s2, v250, 21
	v_cndmask_b32_e32 v149, 0, v207, vcc
	v_cndmask_b32_e32 v148, v0, v206, vcc
	v_mov_b32_e32 v103, s2
	v_readlane_b32 s2, v251, 44
	v_cndmask_b32_e32 v153, v101, v103, vcc
	v_lshlrev_b64 v[148:149], 11, v[148:149]
	v_mov_b32_e32 v101, s2
	v_readlane_b32 s2, v250, 22
	s_nop 1
	v_mov_b32_e32 v103, s2
	v_cndmask_b32_e32 v152, v101, v103, vcc
	v_lshl_add_u64 v[148:149], v[152:153], 0, v[148:149]
	v_mov_b32_e32 v103, v1
	v_lshl_add_u64 v[148:149], v[148:149], 0, v[102:103]
	global_load_dwordx2 v[204:205], v[148:149], off
	global_load_dwordx2 v[202:203], v[148:149], off offset:512
	global_load_dwordx2 v[200:201], v[148:149], off offset:1024
	global_load_dwordx2 v[198:199], v[148:149], off offset:1536
	s_movk_i32 s2, 0x3fff
	v_cmp_lt_i32_e32 vcc, s2, v206
	s_and_saveexec_b64 s[2:3], vcc
	s_xor_b64 s[46:47], exec, s[2:3]
	s_cbranch_execz .LBB0_88
	v_lshlrev_b64 v[148:149], 12, v[0:1]
	v_lshl_add_u64 v[182:183], v[106:107], 0, v[148:149]
	global_load_dwordx4 v[184:187], v[182:183], off
	global_load_dwordx4 v[184:187], v[182:183], off offset:1024
	global_load_dwordx4 v[184:187], v[182:183], off offset:2048
	global_load_dwordx4 v[184:187], v[182:183], off offset:3072
	s_mov_b32 s2, 0x400000
	v_add_co_u32_e32 v206, vcc, s2, v182
	s_nop 1
	v_addc_co_u32_e32 v207, vcc, 0, v183, vcc
	global_load_dwordx4 v[184:187], v[206:207], off
	global_load_dwordx4 v[184:187], v[206:207], off offset:1024
	global_load_dwordx4 v[184:187], v[206:207], off offset:2048
	global_load_dwordx4 v[184:187], v[206:207], off offset:3072
	s_mov_b32 s2, 0x800000
	v_add_co_u32_e32 v206, vcc, s2, v182
	s_nop 1
	v_addc_co_u32_e32 v207, vcc, 0, v183, vcc
	global_load_dwordx4 v[184:187], v[206:207], off
	global_load_dwordx4 v[184:187], v[206:207], off offset:1024
	global_load_dwordx4 v[184:187], v[206:207], off offset:2048
	global_load_dwordx4 v[184:187], v[206:207], off offset:3072
	s_mov_b32 s2, 0xc00000
	v_add_co_u32_e32 v206, vcc, s2, v182
	s_nop 1
	v_addc_co_u32_e32 v207, vcc, 0, v183, vcc
	global_load_dwordx4 v[184:187], v[206:207], off
	global_load_dwordx4 v[184:187], v[206:207], off offset:1024
	global_load_dwordx4 v[184:187], v[206:207], off offset:2048
	global_load_dwordx4 v[184:187], v[206:207], off offset:3072
	s_mov_b32 s2, 0x1000000
	v_add_co_u32_e32 v206, vcc, s2, v182
	s_nop 1
	v_addc_co_u32_e32 v207, vcc, 0, v183, vcc
	global_load_dwordx4 v[184:187], v[206:207], off
	global_load_dwordx4 v[184:187], v[206:207], off offset:1024
	global_load_dwordx4 v[184:187], v[206:207], off offset:2048
	global_load_dwordx4 v[184:187], v[206:207], off offset:3072
	s_mov_b32 s2, 0x1400000
	v_add_co_u32_e32 v206, vcc, s2, v182
	s_nop 1
	v_addc_co_u32_e32 v207, vcc, 0, v183, vcc
	global_load_dwordx4 v[184:187], v[206:207], off
	global_load_dwordx4 v[184:187], v[206:207], off offset:1024
	global_load_dwordx4 v[184:187], v[206:207], off offset:2048
	global_load_dwordx4 v[184:187], v[206:207], off offset:3072
	s_mov_b32 s2, 0x1800000
	v_add_co_u32_e32 v206, vcc, s2, v182
	s_nop 1
	v_addc_co_u32_e32 v207, vcc, 0, v183, vcc
	global_load_dwordx4 v[184:187], v[206:207], off
	global_load_dwordx4 v[184:187], v[206:207], off offset:1024
	global_load_dwordx4 v[184:187], v[206:207], off offset:2048
	global_load_dwordx4 v[184:187], v[206:207], off offset:3072
	global_load_dwordx4 v[184:187], v[182:183], off
	s_mov_b32 s2, 0x400000
	v_add_co_u32_e32 v206, vcc, s2, v182
	s_mov_b32 s2, 0x800000
	s_nop 0
	v_addc_co_u32_e32 v207, vcc, 0, v183, vcc
	s_waitcnt vmcnt(0)
	v_pk_add_f32 v[148:149], v[186:187], 0 op_sel_hi:[1,0]
	v_pk_add_f32 v[152:153], v[184:185], 0 op_sel_hi:[1,0]
	global_load_dwordx4 v[184:187], v[182:183], off offset:1024
	s_waitcnt vmcnt(0)
	v_pk_add_f32 v[154:155], v[186:187], 0 op_sel_hi:[1,0]
	v_pk_add_f32 v[188:189], v[184:185], 0 op_sel_hi:[1,0]
	global_load_dwordx4 v[184:187], v[182:183], off offset:2048
	s_waitcnt vmcnt(0)
	v_pk_add_f32 v[190:191], v[186:187], 0 op_sel_hi:[1,0]
	v_pk_add_f32 v[192:193], v[184:185], 0 op_sel_hi:[1,0]
	global_load_dwordx4 v[184:187], v[182:183], off offset:3072
	s_waitcnt vmcnt(0)
	v_pk_add_f32 v[194:195], v[186:187], 0 op_sel_hi:[1,0]
	v_pk_add_f32 v[196:197], v[184:185], 0 op_sel_hi:[1,0]
	global_load_dwordx4 v[184:187], v[206:207], off
	s_waitcnt vmcnt(0)
	v_pk_add_f32 v[148:149], v[148:149], v[186:187]
	v_pk_add_f32 v[152:153], v[152:153], v[184:185]
	global_load_dwordx4 v[184:187], v[206:207], off offset:1024
	s_waitcnt vmcnt(0)
	v_pk_add_f32 v[154:155], v[154:155], v[186:187]
	v_pk_add_f32 v[188:189], v[188:189], v[184:185]
	global_load_dwordx4 v[184:187], v[206:207], off offset:2048
	s_waitcnt vmcnt(0)
	v_pk_add_f32 v[190:191], v[190:191], v[186:187]
	v_pk_add_f32 v[192:193], v[192:193], v[184:185]
	global_load_dwordx4 v[184:187], v[206:207], off offset:3072
	v_add_co_u32_e32 v206, vcc, s2, v182
	s_mov_b32 s2, 0xc00000
	s_nop 0
	v_addc_co_u32_e32 v207, vcc, 0, v183, vcc
	s_waitcnt vmcnt(0)
	v_pk_add_f32 v[194:195], v[194:195], v[186:187]
	v_pk_add_f32 v[196:197], v[196:197], v[184:185]
	global_load_dwordx4 v[184:187], v[206:207], off
	s_waitcnt vmcnt(0)
	v_pk_add_f32 v[148:149], v[148:149], v[186:187]
	v_pk_add_f32 v[152:153], v[152:153], v[184:185]
	global_load_dwordx4 v[184:187], v[206:207], off offset:1024
	s_waitcnt vmcnt(0)
	v_pk_add_f32 v[154:155], v[154:155], v[186:187]
	v_pk_add_f32 v[188:189], v[188:189], v[184:185]
	global_load_dwordx4 v[184:187], v[206:207], off offset:2048
	s_waitcnt vmcnt(0)
	v_pk_add_f32 v[190:191], v[190:191], v[186:187]
	v_pk_add_f32 v[192:193], v[192:193], v[184:185]
	global_load_dwordx4 v[184:187], v[206:207], off offset:3072
	v_add_co_u32_e32 v206, vcc, s2, v182
	s_mov_b32 s2, 0x1000000
	s_nop 0
	v_addc_co_u32_e32 v207, vcc, 0, v183, vcc
	s_waitcnt vmcnt(0)
	v_pk_add_f32 v[194:195], v[194:195], v[186:187]
	v_pk_add_f32 v[196:197], v[196:197], v[184:185]
	global_load_dwordx4 v[184:187], v[206:207], off
	s_waitcnt vmcnt(0)
	v_pk_add_f32 v[148:149], v[148:149], v[186:187]
	v_pk_add_f32 v[152:153], v[152:153], v[184:185]
	global_load_dwordx4 v[184:187], v[206:207], off offset:1024
	s_waitcnt vmcnt(0)
	v_pk_add_f32 v[154:155], v[154:155], v[186:187]
	v_pk_add_f32 v[188:189], v[188:189], v[184:185]
	global_load_dwordx4 v[184:187], v[206:207], off offset:2048
	s_waitcnt vmcnt(0)
	v_pk_add_f32 v[190:191], v[190:191], v[186:187]
	v_pk_add_f32 v[192:193], v[192:193], v[184:185]
	global_load_dwordx4 v[184:187], v[206:207], off offset:3072
	v_add_co_u32_e32 v206, vcc, s2, v182
	s_mov_b32 s2, 0x1400000
	s_nop 0
	v_addc_co_u32_e32 v207, vcc, 0, v183, vcc
	s_waitcnt vmcnt(0)
	v_pk_add_f32 v[194:195], v[194:195], v[186:187]
	v_pk_add_f32 v[196:197], v[196:197], v[184:185]
	global_load_dwordx4 v[184:187], v[206:207], off
	s_waitcnt vmcnt(0)
	v_pk_add_f32 v[148:149], v[148:149], v[186:187]
	v_pk_add_f32 v[152:153], v[152:153], v[184:185]
	global_load_dwordx4 v[184:187], v[206:207], off offset:1024
	s_waitcnt vmcnt(0)
	v_pk_add_f32 v[154:155], v[154:155], v[186:187]
	v_pk_add_f32 v[188:189], v[188:189], v[184:185]
	global_load_dwordx4 v[184:187], v[206:207], off offset:2048
	s_waitcnt vmcnt(0)
	v_pk_add_f32 v[190:191], v[190:191], v[186:187]
	v_pk_add_f32 v[192:193], v[192:193], v[184:185]
	global_load_dwordx4 v[184:187], v[206:207], off offset:3072
	v_add_co_u32_e32 v206, vcc, s2, v182
	s_mov_b32 s2, 0x1800000
	s_nop 0
	v_addc_co_u32_e32 v207, vcc, 0, v183, vcc
	s_waitcnt vmcnt(0)
	v_pk_add_f32 v[194:195], v[194:195], v[186:187]
	v_pk_add_f32 v[196:197], v[196:197], v[184:185]
	global_load_dwordx4 v[184:187], v[206:207], off
	s_waitcnt vmcnt(0)
	v_pk_add_f32 v[148:149], v[148:149], v[186:187]
	v_pk_add_f32 v[152:153], v[152:153], v[184:185]
	global_load_dwordx4 v[184:187], v[206:207], off offset:1024
	s_waitcnt vmcnt(0)
	v_pk_add_f32 v[154:155], v[154:155], v[186:187]
	v_pk_add_f32 v[226:227], v[188:189], v[184:185]
	global_load_dwordx4 v[184:187], v[206:207], off offset:2048
	s_waitcnt vmcnt(0)
	v_pk_add_f32 v[230:231], v[190:191], v[186:187]
	v_pk_add_f32 v[192:193], v[192:193], v[184:185]
	global_load_dwordx4 v[184:187], v[206:207], off offset:3072
	v_add_co_u32_e32 v206, vcc, s2, v182
	s_waitcnt vmcnt(0)
	v_pk_add_f32 v[194:195], v[194:195], v[186:187]
	v_addc_co_u32_e32 v207, vcc, 0, v183, vcc
	v_pk_add_f32 v[196:197], v[196:197], v[184:185]
	global_load_dwordx4 v[184:187], v[206:207], off
	global_load_dwordx4 v[188:191], v[206:207], off offset:1024
	s_waitcnt vmcnt(1)
	v_pk_add_f32 v[182:183], v[148:149], v[186:187]
	s_waitcnt vmcnt(0)
	v_pk_add_f32 v[188:189], v[226:227], v[188:189]
	global_load_dwordx4 v[226:229], v[206:207], off offset:2048
	v_pk_add_f32 v[186:187], v[154:155], v[190:191]
	v_pk_add_f32 v[184:185], v[152:153], v[184:185]
	s_waitcnt vmcnt(0)
	v_pk_add_f32 v[190:191], v[230:231], v[228:229]
	v_pk_add_f32 v[192:193], v[192:193], v[226:227]
	global_load_dwordx4 v[226:229], v[206:207], off offset:3072
	s_waitcnt vmcnt(0)
	v_pk_add_f32 v[194:195], v[194:195], v[228:229]
	v_pk_add_f32 v[196:197], v[196:197], v[226:227]

.LBB0_178:
	s_and_saveexec_b64 s[2:3], s[44:45]
	s_xor_b64 s[26:27], exec, s[2:3]
	s_cbranch_execz .LBB0_180
	v_readlane_b32 s2, v251, 62
	v_mov_b32_e32 v157, v1
	v_readlane_b32 s3, v251, 63
	v_lshlrev_b64 v[36:37], 12, v[0:1]
	s_nop 0
	v_lshl_add_u64 v[2:3], s[2:3], 0, v[156:157]
	v_lshl_add_u64 v[2:3], v[2:3], 0, v[36:37]
	global_load_dwordx4 v[36:39], v[2:3], off
	global_load_dwordx4 v[36:39], v[2:3], off offset:1024
	global_load_dwordx4 v[36:39], v[2:3], off offset:2048
	global_load_dwordx4 v[36:39], v[2:3], off offset:3072
	s_mov_b32 s2, 0x400000
	v_add_co_u32_e32 v74, vcc, s2, v2
	s_nop 1
	v_addc_co_u32_e32 v75, vcc, 0, v3, vcc
	global_load_dwordx4 v[36:39], v[74:75], off
	global_load_dwordx4 v[36:39], v[74:75], off offset:1024
	global_load_dwordx4 v[36:39], v[74:75], off offset:2048
	global_load_dwordx4 v[36:39], v[74:75], off offset:3072
	s_mov_b32 s2, 0x800000
	v_add_co_u32_e32 v74, vcc, s2, v2
	s_nop 1
	v_addc_co_u32_e32 v75, vcc, 0, v3, vcc
	global_load_dwordx4 v[36:39], v[74:75], off
	global_load_dwordx4 v[36:39], v[74:75], off offset:1024
	global_load_dwordx4 v[36:39], v[74:75], off offset:2048
	global_load_dwordx4 v[36:39], v[74:75], off offset:3072
	s_mov_b32 s2, 0xc00000
	v_add_co_u32_e32 v74, vcc, s2, v2
	s_nop 1
	v_addc_co_u32_e32 v75, vcc, 0, v3, vcc
	global_load_dwordx4 v[36:39], v[74:75], off
	global_load_dwordx4 v[36:39], v[74:75], off offset:1024
	global_load_dwordx4 v[36:39], v[74:75], off offset:2048
	global_load_dwordx4 v[36:39], v[74:75], off offset:3072
	global_load_dwordx4 v[36:39], v[2:3], off
	s_mov_b32 s2, 0x400000
	v_add_co_u32_e32 v74, vcc, s2, v2
	s_mov_b32 s2, 0x800000
	s_nop 0
	v_addc_co_u32_e32 v75, vcc, 0, v3, vcc
	s_waitcnt vmcnt(0)
	v_pk_add_f32 v[40:41], v[38:39], 0 op_sel_hi:[1,0]
	v_pk_add_f32 v[42:43], v[36:37], 0 op_sel_hi:[1,0]
	global_load_dwordx4 v[36:39], v[2:3], off offset:1024
	s_waitcnt vmcnt(0)
	v_pk_add_f32 v[44:45], v[38:39], 0 op_sel_hi:[1,0]
	v_pk_add_f32 v[46:47], v[36:37], 0 op_sel_hi:[1,0]
	global_load_dwordx4 v[36:39], v[2:3], off offset:2048
	s_waitcnt vmcnt(0)
	v_pk_add_f32 v[48:49], v[38:39], 0 op_sel_hi:[1,0]
	v_pk_add_f32 v[50:51], v[36:37], 0 op_sel_hi:[1,0]
	global_load_dwordx4 v[36:39], v[2:3], off offset:3072
	s_waitcnt vmcnt(0)
	v_pk_add_f32 v[68:69], v[38:39], 0 op_sel_hi:[1,0]
	v_pk_add_f32 v[70:71], v[36:37], 0 op_sel_hi:[1,0]
	global_load_dwordx4 v[36:39], v[74:75], off
	s_waitcnt vmcnt(0)
	v_pk_add_f32 v[40:41], v[40:41], v[38:39]
	v_pk_add_f32 v[42:43], v[42:43], v[36:37]
	global_load_dwordx4 v[36:39], v[74:75], off offset:1024
	s_waitcnt vmcnt(0)
	v_pk_add_f32 v[44:45], v[44:45], v[38:39]
	v_pk_add_f32 v[46:47], v[46:47], v[36:37]
	global_load_dwordx4 v[36:39], v[74:75], off offset:2048
	s_waitcnt vmcnt(0)
	v_pk_add_f32 v[48:49], v[48:49], v[38:39]
	v_pk_add_f32 v[50:51], v[50:51], v[36:37]
	global_load_dwordx4 v[36:39], v[74:75], off offset:3072
	v_add_co_u32_e32 v74, vcc, s2, v2
	s_mov_b32 s2, 0xc00000
	s_nop 0
	v_addc_co_u32_e32 v75, vcc, 0, v3, vcc
	v_add_co_u32_e32 v2, vcc, s2, v2
	s_waitcnt vmcnt(0)
	v_pk_add_f32 v[68:69], v[68:69], v[38:39]
	v_pk_add_f32 v[70:71], v[70:71], v[36:37]
	global_load_dwordx4 v[36:39], v[74:75], off
	v_addc_co_u32_e32 v3, vcc, 0, v3, vcc
	s_waitcnt vmcnt(0)
	v_pk_add_f32 v[40:41], v[40:41], v[38:39]
	v_pk_add_f32 v[42:43], v[42:43], v[36:37]
	global_load_dwordx4 v[36:39], v[74:75], off offset:1024
	s_waitcnt vmcnt(0)
	v_pk_add_f32 v[44:45], v[44:45], v[38:39]
	v_pk_add_f32 v[46:47], v[46:47], v[36:37]
	global_load_dwordx4 v[36:39], v[74:75], off offset:2048
	s_waitcnt vmcnt(0)
	v_pk_add_f32 v[48:49], v[48:49], v[38:39]
	v_pk_add_f32 v[50:51], v[50:51], v[36:37]
	global_load_dwordx4 v[36:39], v[74:75], off offset:3072
	s_waitcnt vmcnt(0)
	v_pk_add_f32 v[68:69], v[68:69], v[38:39]
	v_pk_add_f32 v[70:71], v[70:71], v[36:37]
	global_load_dwordx4 v[36:39], v[2:3], off
	s_waitcnt vmcnt(0)
	v_pk_add_f32 v[188:189], v[40:41], v[38:39]
	v_pk_add_f32 v[190:191], v[42:43], v[36:37]
	global_load_dwordx4 v[36:39], v[2:3], off offset:1024
	s_waitcnt vmcnt(0)
	v_pk_add_f32 v[184:185], v[44:45], v[38:39]
	v_pk_add_f32 v[186:187], v[46:47], v[36:37]
	global_load_dwordx4 v[36:39], v[2:3], off offset:2048
	s_waitcnt vmcnt(0)
	v_pk_add_f32 v[180:181], v[48:49], v[38:39]
	v_pk_add_f32 v[182:183], v[50:51], v[36:37]
	global_load_dwordx4 v[36:39], v[2:3], off offset:3072
	s_waitcnt vmcnt(0)
	v_pk_add_f32 v[196:197], v[68:69], v[38:39]
	v_pk_add_f32 v[198:199], v[70:71], v[36:37]
	s_andn2_saveexec_b64 s[26:27], s[26:27]
	s_cbranch_execnz .LBB0_181
	s_branch .LBB0_182

.LBB0_188:
	s_and_saveexec_b64 s[2:3], s[44:45]
	s_xor_b64 s[26:27], exec, s[2:3]
	s_cbranch_execz .LBB0_190
	v_readlane_b32 s2, v251, 62
	v_mov_b32_e32 v157, v1
	v_readlane_b32 s3, v251, 63
	v_lshlrev_b64 v[68:69], 12, v[0:1]
	s_nop 0
	v_lshl_add_u64 v[2:3], s[2:3], 0, v[156:157]
	v_lshl_add_u64 v[2:3], v[2:3], 0, v[68:69]
	global_load_dwordx4 v[68:71], v[2:3], off
	global_load_dwordx4 v[68:71], v[2:3], off offset:1024
	global_load_dwordx4 v[68:71], v[2:3], off offset:2048
	global_load_dwordx4 v[68:71], v[2:3], off offset:3072
	s_mov_b32 s2, 0x400000
	v_add_co_u32_e32 v90, vcc, s2, v2
	s_nop 1
	v_addc_co_u32_e32 v91, vcc, 0, v3, vcc
	global_load_dwordx4 v[68:71], v[90:91], off
	global_load_dwordx4 v[68:71], v[90:91], off offset:1024
	global_load_dwordx4 v[68:71], v[90:91], off offset:2048
	global_load_dwordx4 v[68:71], v[90:91], off offset:3072
	s_mov_b32 s2, 0x800000
	v_add_co_u32_e32 v90, vcc, s2, v2
	s_nop 1
	v_addc_co_u32_e32 v91, vcc, 0, v3, vcc
	global_load_dwordx4 v[68:71], v[90:91], off
	global_load_dwordx4 v[68:71], v[90:91], off offset:1024
	global_load_dwordx4 v[68:71], v[90:91], off offset:2048
	global_load_dwordx4 v[68:71], v[90:91], off offset:3072
	s_mov_b32 s2, 0xc00000
	v_add_co_u32_e32 v90, vcc, s2, v2
	s_nop 1
	v_addc_co_u32_e32 v91, vcc, 0, v3, vcc
	global_load_dwordx4 v[68:71], v[90:91], off
	global_load_dwordx4 v[68:71], v[90:91], off offset:1024
	global_load_dwordx4 v[68:71], v[90:91], off offset:2048
	global_load_dwordx4 v[68:71], v[90:91], off offset:3072
	global_load_dwordx4 v[68:71], v[2:3], off
	s_mov_b32 s2, 0x400000
	v_add_co_u32_e32 v90, vcc, s2, v2
	s_mov_b32 s2, 0x800000
	s_nop 0
	v_addc_co_u32_e32 v91, vcc, 0, v3, vcc
	s_waitcnt vmcnt(0)
	v_pk_add_f32 v[74:75], v[70:71], 0 op_sel_hi:[1,0]
	v_pk_add_f32 v[76:77], v[68:69], 0 op_sel_hi:[1,0]
	global_load_dwordx4 v[68:71], v[2:3], off offset:1024
	s_waitcnt vmcnt(0)
	v_pk_add_f32 v[78:79], v[70:71], 0 op_sel_hi:[1,0]
	v_pk_add_f32 v[80:81], v[68:69], 0 op_sel_hi:[1,0]
	global_load_dwordx4 v[68:71], v[2:3], off offset:2048
	s_waitcnt vmcnt(0)
	v_pk_add_f32 v[82:83], v[70:71], 0 op_sel_hi:[1,0]
	v_pk_add_f32 v[84:85], v[68:69], 0 op_sel_hi:[1,0]
	global_load_dwordx4 v[68:71], v[2:3], off offset:3072
	s_waitcnt vmcnt(0)
	v_pk_add_f32 v[86:87], v[70:71], 0 op_sel_hi:[1,0]
	v_pk_add_f32 v[88:89], v[68:69], 0 op_sel_hi:[1,0]
	global_load_dwordx4 v[68:71], v[90:91], off
	s_waitcnt vmcnt(0)
	v_pk_add_f32 v[74:75], v[74:75], v[70:71]
	v_pk_add_f32 v[76:77], v[76:77], v[68:69]
	global_load_dwordx4 v[68:71], v[90:91], off offset:1024
	s_waitcnt vmcnt(0)
	v_pk_add_f32 v[78:79], v[78:79], v[70:71]
	v_pk_add_f32 v[80:81], v[80:81], v[68:69]
	global_load_dwordx4 v[68:71], v[90:91], off offset:2048
	s_waitcnt vmcnt(0)
	v_pk_add_f32 v[82:83], v[82:83], v[70:71]
	v_pk_add_f32 v[84:85], v[84:85], v[68:69]
	global_load_dwordx4 v[68:71], v[90:91], off offset:3072
	v_add_co_u32_e32 v90, vcc, s2, v2
	s_mov_b32 s2, 0xc00000
	s_nop 0
	v_addc_co_u32_e32 v91, vcc, 0, v3, vcc
	v_add_co_u32_e32 v2, vcc, s2, v2
	s_waitcnt vmcnt(0)
	v_pk_add_f32 v[86:87], v[86:87], v[70:71]
	v_pk_add_f32 v[88:89], v[88:89], v[68:69]
	global_load_dwordx4 v[68:71], v[90:91], off
	v_addc_co_u32_e32 v3, vcc, 0, v3, vcc
	s_waitcnt vmcnt(0)
	v_pk_add_f32 v[74:75], v[74:75], v[70:71]
	v_pk_add_f32 v[76:77], v[76:77], v[68:69]
	global_load_dwordx4 v[68:71], v[90:91], off offset:1024
	s_waitcnt vmcnt(0)
	v_pk_add_f32 v[78:79], v[78:79], v[70:71]
	v_pk_add_f32 v[80:81], v[80:81], v[68:69]
	global_load_dwordx4 v[68:71], v[90:91], off offset:2048
	s_waitcnt vmcnt(0)
	v_pk_add_f32 v[82:83], v[82:83], v[70:71]
	v_pk_add_f32 v[84:85], v[84:85], v[68:69]
	global_load_dwordx4 v[68:71], v[90:91], off offset:3072
	s_waitcnt vmcnt(0)
	v_pk_add_f32 v[86:87], v[86:87], v[70:71]
	v_pk_add_f32 v[88:89], v[88:89], v[68:69]
	global_load_dwordx4 v[68:71], v[2:3], off
	s_waitcnt vmcnt(0)
	v_pk_add_f32 v[168:169], v[74:75], v[70:71]
	v_pk_add_f32 v[170:171], v[76:77], v[68:69]
	global_load_dwordx4 v[68:71], v[2:3], off offset:1024
	s_waitcnt vmcnt(0)
	v_pk_add_f32 v[172:173], v[78:79], v[70:71]
	v_pk_add_f32 v[174:175], v[80:81], v[68:69]
	global_load_dwordx4 v[68:71], v[2:3], off offset:2048
	s_waitcnt vmcnt(0)
	v_pk_add_f32 v[176:177], v[82:83], v[70:71]
	v_pk_add_f32 v[178:179], v[84:85], v[68:69]
	global_load_dwordx4 v[68:71], v[2:3], off offset:3072
	s_waitcnt vmcnt(0)
	v_pk_add_f32 v[192:193], v[86:87], v[70:71]
	v_pk_add_f32 v[194:195], v[88:89], v[68:69]
	s_andn2_saveexec_b64 s[26:27], s[26:27]
	s_cbranch_execnz .LBB0_191
	s_branch .LBB0_192

.LBB0_202:
	s_and_saveexec_b64 s[2:3], s[42:43]
	s_xor_b64 s[26:27], exec, s[2:3]
	s_cbranch_execz .LBB0_204
	v_lshlrev_b64 v[2:3], 12, v[0:1]
	v_lshl_add_u64 v[2:3], v[160:161], 0, v[2:3]
	global_load_dwordx4 v[132:135], v[2:3], off
	global_load_dwordx4 v[132:135], v[2:3], off offset:1024
	global_load_dwordx4 v[132:135], v[2:3], off offset:2048
	global_load_dwordx4 v[132:135], v[2:3], off offset:3072
	s_mov_b32 s2, 0x400000
	v_add_co_u32_e32 v204, vcc, s2, v2
	s_nop 1
	v_addc_co_u32_e32 v205, vcc, 0, v3, vcc
	global_load_dwordx4 v[132:135], v[204:205], off
	global_load_dwordx4 v[132:135], v[204:205], off offset:1024
	global_load_dwordx4 v[132:135], v[204:205], off offset:2048
	global_load_dwordx4 v[132:135], v[204:205], off offset:3072
	s_mov_b32 s2, 0x800000
	v_add_co_u32_e32 v204, vcc, s2, v2
	s_nop 1
	v_addc_co_u32_e32 v205, vcc, 0, v3, vcc
	global_load_dwordx4 v[132:135], v[204:205], off
	global_load_dwordx4 v[132:135], v[204:205], off offset:1024
	global_load_dwordx4 v[132:135], v[204:205], off offset:2048
	global_load_dwordx4 v[132:135], v[204:205], off offset:3072
	s_mov_b32 s2, 0xc00000
	v_add_co_u32_e32 v204, vcc, s2, v2
	s_nop 1
	v_addc_co_u32_e32 v205, vcc, 0, v3, vcc
	global_load_dwordx4 v[132:135], v[204:205], off
	global_load_dwordx4 v[132:135], v[204:205], off offset:1024
	global_load_dwordx4 v[132:135], v[204:205], off offset:2048
	global_load_dwordx4 v[132:135], v[204:205], off offset:3072
	global_load_dwordx4 v[132:135], v[2:3], off
	s_mov_b32 s2, 0x400000
	v_add_co_u32_e32 v204, vcc, s2, v2
	s_mov_b32 s2, 0x800000
	s_nop 0
	v_addc_co_u32_e32 v205, vcc, 0, v3, vcc
	s_waitcnt vmcnt(0)
	v_pk_add_f32 v[136:137], v[134:135], 0 op_sel_hi:[1,0]
	v_pk_add_f32 v[138:139], v[132:133], 0 op_sel_hi:[1,0]
	global_load_dwordx4 v[132:135], v[2:3], off offset:1024
	s_waitcnt vmcnt(0)
	v_pk_add_f32 v[140:141], v[134:135], 0 op_sel_hi:[1,0]
	v_pk_add_f32 v[142:143], v[132:133], 0 op_sel_hi:[1,0]
	global_load_dwordx4 v[132:135], v[2:3], off offset:2048
	s_waitcnt vmcnt(0)
	v_pk_add_f32 v[144:145], v[134:135], 0 op_sel_hi:[1,0]
	v_pk_add_f32 v[146:147], v[132:133], 0 op_sel_hi:[1,0]
	global_load_dwordx4 v[132:135], v[2:3], off offset:3072
	s_waitcnt vmcnt(0)
	v_pk_add_f32 v[200:201], v[134:135], 0 op_sel_hi:[1,0]
	v_pk_add_f32 v[202:203], v[132:133], 0 op_sel_hi:[1,0]
	global_load_dwordx4 v[132:135], v[204:205], off
	s_waitcnt vmcnt(0)
	v_pk_add_f32 v[136:137], v[136:137], v[134:135]
	v_pk_add_f32 v[138:139], v[138:139], v[132:133]
	global_load_dwordx4 v[132:135], v[204:205], off offset:1024
	s_waitcnt vmcnt(0)
	v_pk_add_f32 v[140:141], v[140:141], v[134:135]
	v_pk_add_f32 v[142:143], v[142:143], v[132:133]
	global_load_dwordx4 v[132:135], v[204:205], off offset:2048
	s_waitcnt vmcnt(0)
	v_pk_add_f32 v[144:145], v[144:145], v[134:135]
	v_pk_add_f32 v[146:147], v[146:147], v[132:133]
	global_load_dwordx4 v[132:135], v[204:205], off offset:3072
	v_add_co_u32_e32 v204, vcc, s2, v2
	s_mov_b32 s2, 0xc00000
	s_nop 0
	v_addc_co_u32_e32 v205, vcc, 0, v3, vcc
	v_add_co_u32_e32 v214, vcc, s2, v2
	s_waitcnt vmcnt(0)
	v_pk_add_f32 v[200:201], v[200:201], v[134:135]
	v_pk_add_f32 v[202:203], v[202:203], v[132:133]
	global_load_dwordx4 v[132:135], v[204:205], off
	v_addc_co_u32_e32 v215, vcc, 0, v3, vcc
	s_waitcnt vmcnt(0)
	v_pk_add_f32 v[136:137], v[136:137], v[134:135]
	v_pk_add_f32 v[138:139], v[138:139], v[132:133]
	global_load_dwordx4 v[132:135], v[204:205], off offset:1024
	s_waitcnt vmcnt(0)
	v_pk_add_f32 v[140:141], v[140:141], v[134:135]
	v_pk_add_f32 v[142:143], v[142:143], v[132:133]
	global_load_dwordx4 v[132:135], v[204:205], off offset:2048
	s_waitcnt vmcnt(0)
	v_pk_add_f32 v[144:145], v[144:145], v[134:135]
	v_pk_add_f32 v[146:147], v[146:147], v[132:133]
	global_load_dwordx4 v[132:135], v[204:205], off offset:3072
	s_waitcnt vmcnt(0)
	v_pk_add_f32 v[210:211], v[200:201], v[134:135]
	v_pk_add_f32 v[212:213], v[202:203], v[132:133]
	global_load_dwordx4 v[132:135], v[214:215], off
	s_waitcnt vmcnt(0)
	v_pk_add_f32 v[2:3], v[136:137], v[134:135]
	v_pk_add_f32 v[200:201], v[138:139], v[132:133]
	global_load_dwordx4 v[132:135], v[214:215], off offset:1024
	s_waitcnt vmcnt(0)
	v_pk_add_f32 v[202:203], v[140:141], v[134:135]
	v_pk_add_f32 v[204:205], v[142:143], v[132:133]
	global_load_dwordx4 v[132:135], v[214:215], off offset:2048
	s_waitcnt vmcnt(0)
	v_pk_add_f32 v[206:207], v[144:145], v[134:135]
	v_pk_add_f32 v[208:209], v[146:147], v[132:133]
	global_load_dwordx4 v[132:135], v[214:215], off offset:3072
	s_waitcnt vmcnt(0)
	v_pk_add_f32 v[210:211], v[210:211], v[134:135]
	v_pk_add_f32 v[212:213], v[212:213], v[132:133]
	s_andn2_saveexec_b64 s[26:27], s[26:27]
	s_cbranch_execnz .LBB0_205
	s_branch .LBB0_206

.LBB0_212:
	s_and_saveexec_b64 s[2:3], s[42:43]
	s_xor_b64 s[26:27], exec, s[2:3]
	s_cbranch_execz .LBB0_214
	v_lshlrev_b64 v[214:215], 12, v[0:1]
	v_lshl_add_u64 v[218:219], v[160:161], 0, v[214:215]
	global_load_dwordx4 v[214:217], v[218:219], off
	global_load_dwordx4 v[214:217], v[218:219], off offset:1024
	global_load_dwordx4 v[214:217], v[218:219], off offset:2048
	global_load_dwordx4 v[214:217], v[218:219], off offset:3072
	s_mov_b32 s2, 0x400000
	v_add_co_u32_e32 v148, vcc, s2, v218
	s_nop 1
	v_addc_co_u32_e32 v149, vcc, 0, v219, vcc
	global_load_dwordx4 v[214:217], v[148:149], off
	global_load_dwordx4 v[214:217], v[148:149], off offset:1024
	global_load_dwordx4 v[214:217], v[148:149], off offset:2048
	global_load_dwordx4 v[214:217], v[148:149], off offset:3072
	s_mov_b32 s2, 0x800000
	v_add_co_u32_e32 v148, vcc, s2, v218
	s_nop 1
	v_addc_co_u32_e32 v149, vcc, 0, v219, vcc
	global_load_dwordx4 v[214:217], v[148:149], off
	global_load_dwordx4 v[214:217], v[148:149], off offset:1024
	global_load_dwordx4 v[214:217], v[148:149], off offset:2048
	global_load_dwordx4 v[214:217], v[148:149], off offset:3072
	s_mov_b32 s2, 0xc00000
	v_add_co_u32_e32 v148, vcc, s2, v218
	s_nop 1
	v_addc_co_u32_e32 v149, vcc, 0, v219, vcc
	global_load_dwordx4 v[214:217], v[148:149], off
	global_load_dwordx4 v[214:217], v[148:149], off offset:1024
	global_load_dwordx4 v[214:217], v[148:149], off offset:2048
	global_load_dwordx4 v[214:217], v[148:149], off offset:3072
	global_load_dwordx4 v[214:217], v[218:219], off
	s_mov_b32 s2, 0x400000
	v_add_co_u32_e32 v148, vcc, s2, v218
	s_mov_b32 s2, 0x800000
	s_nop 0
	v_addc_co_u32_e32 v149, vcc, 0, v219, vcc
	s_waitcnt vmcnt(0)
	v_pk_add_f32 v[220:221], v[216:217], 0 op_sel_hi:[1,0]
	v_pk_add_f32 v[222:223], v[214:215], 0 op_sel_hi:[1,0]
	global_load_dwordx4 v[214:217], v[218:219], off offset:1024
	s_waitcnt vmcnt(0)
	v_pk_add_f32 v[224:225], v[216:217], 0 op_sel_hi:[1,0]
	v_pk_add_f32 v[226:227], v[214:215], 0 op_sel_hi:[1,0]
	global_load_dwordx4 v[214:217], v[218:219], off offset:2048
	s_waitcnt vmcnt(0)
	v_pk_add_f32 v[228:229], v[216:217], 0 op_sel_hi:[1,0]
	v_pk_add_f32 v[230:231], v[214:215], 0 op_sel_hi:[1,0]
	global_load_dwordx4 v[214:217], v[218:219], off offset:3072
	s_waitcnt vmcnt(0)
	v_pk_add_f32 v[152:153], v[216:217], 0 op_sel_hi:[1,0]
	v_pk_add_f32 v[154:155], v[214:215], 0 op_sel_hi:[1,0]
	global_load_dwordx4 v[214:217], v[148:149], off
	s_waitcnt vmcnt(0)
	v_pk_add_f32 v[220:221], v[220:221], v[216:217]
	v_pk_add_f32 v[222:223], v[222:223], v[214:215]
	global_load_dwordx4 v[214:217], v[148:149], off offset:1024
	s_waitcnt vmcnt(0)
	v_pk_add_f32 v[224:225], v[224:225], v[216:217]
	v_pk_add_f32 v[226:227], v[226:227], v[214:215]
	global_load_dwordx4 v[214:217], v[148:149], off offset:2048
	s_waitcnt vmcnt(0)
	v_pk_add_f32 v[228:229], v[228:229], v[216:217]
	v_pk_add_f32 v[230:231], v[230:231], v[214:215]
	global_load_dwordx4 v[214:217], v[148:149], off offset:3072
	s_waitcnt vmcnt(0)
	v_pk_add_f32 v[148:149], v[152:153], v[216:217]
	v_pk_add_f32 v[152:153], v[154:155], v[214:215]
	v_add_co_u32_e32 v154, vcc, s2, v218
	s_mov_b32 s2, 0xc00000
	s_nop 0
	v_addc_co_u32_e32 v155, vcc, 0, v219, vcc
	global_load_dwordx4 v[214:217], v[154:155], off
	s_waitcnt vmcnt(0)
	v_pk_add_f32 v[220:221], v[220:221], v[216:217]
	v_pk_add_f32 v[222:223], v[222:223], v[214:215]
	global_load_dwordx4 v[214:217], v[154:155], off offset:1024
	s_waitcnt vmcnt(0)
	v_pk_add_f32 v[224:225], v[224:225], v[216:217]
	v_pk_add_f32 v[226:227], v[226:227], v[214:215]
	global_load_dwordx4 v[214:217], v[154:155], off offset:2048
	s_waitcnt vmcnt(0)
	v_pk_add_f32 v[228:229], v[228:229], v[216:217]
	v_pk_add_f32 v[230:231], v[230:231], v[214:215]
	global_load_dwordx4 v[214:217], v[154:155], off offset:3072
	v_add_co_u32_e32 v154, vcc, s2, v218
	s_waitcnt vmcnt(0)
	v_pk_add_f32 v[148:149], v[148:149], v[216:217]
	v_addc_co_u32_e32 v155, vcc, 0, v219, vcc
	global_load_dwordx4 v[216:219], v[154:155], off
	v_pk_add_f32 v[152:153], v[152:153], v[214:215]
	s_waitcnt vmcnt(0)
	v_pk_add_f32 v[214:215], v[220:221], v[218:219]
	v_pk_add_f32 v[216:217], v[222:223], v[216:217]
	global_load_dwordx4 v[220:223], v[154:155], off offset:1024
	s_waitcnt vmcnt(0)
	v_pk_add_f32 v[218:219], v[224:225], v[222:223]
	v_pk_add_f32 v[220:221], v[226:227], v[220:221]
	global_load_dwordx4 v[224:227], v[154:155], off offset:2048
	s_waitcnt vmcnt(0)
	v_pk_add_f32 v[222:223], v[228:229], v[226:227]
	v_pk_add_f32 v[224:225], v[230:231], v[224:225]
	global_load_dwordx4 v[228:231], v[154:155], off offset:3072
	s_waitcnt vmcnt(0)
	v_pk_add_f32 v[226:227], v[148:149], v[230:231]
	v_pk_add_f32 v[228:229], v[152:153], v[228:229]
	s_andn2_saveexec_b64 s[26:27], s[26:27]
	s_cbranch_execnz .LBB0_215
	s_branch .LBB0_216
